# phase 0 w_in transposes: each item prefetches the block's next item's four loads into shadow registers
# baseline (speedup 1.0000x reference)
; DI int tidx() { int t = threadIdx.x; asm volatile("" : "+v"(t)); return t; }
; DI void transpose_item(const float* __restrict__ W, u16* __restrict__ Wt, int N, int kt, int nt2, char* lds) {
;   const int tid512 = tidx();
;   const int hb = tid512 >> 8, tid = tid512 & 255, nt = nt2 * 2 + hb;
;   u16* tile = (u16*)lds + hb * (64 * 72);
;   {
;     const int r = tid >> 2, cs = (tid & 3) * 16;
;     const float* src = W + (size_t)(kt * 64 + r) * N + nt * 64 + cs;
;     float4 v[4];
; #pragma unroll
;     for (int q = 0; q < 4; ++q) v[q] = *(const float4*)(src + q * 4);
; #pragma unroll
;     for (int q = 0; q < 4; ++q) {
;       const unsigned u01 = pack2(v[q].x, v[q].y), u23 = pack2(v[q].z, v[q].w);
;       tile[(cs + q * 4 + 0) * 72 + r] = (u16)u01;
;       tile[(cs + q * 4 + 1) * 72 + r] = (u16)(u01 >> 16);
;       tile[(cs + q * 4 + 2) * 72 + r] = (u16)u23;
;       tile[(cs + q * 4 + 3) * 72 + r] = (u16)(u23 >> 16);
;     }
;   }
; DI void phase_prep(const P& p, char* lds) {
;   for (int it = blockIdx.x; it < 192 + 960 + 256; it += gridDim.x) {
;     if (it < 192) {
;       mod_item(p, it, lds);
;     } else if (it < 192 + 960) {
;       int t = it - 192;
;       int l = t / 480, rem = t % 480;
;       int kt = rem / 30, nt2 = rem % 30;
;       transpose_item(p.w_in + (size_t)l * 1024 * NIN, p.Wt + (size_t)l * NIN * 1024, NIN, kt, nt2, lds);
.LBB0_964:
	s_andn2_b64 vcc, exec, s[0:1]
	s_cbranch_vccnz .LBB0_966
	s_add_i32 s0, s23, 0xffffff40
	s_add_i32 s1, s23, 0xfffffd60
	s_cmpk_lt_u32 s0, 0x1e0
	s_cselect_b32 s1, s0, s1
	s_mul_hi_u32 s2, s1, 0x88888889
	s_lshr_b32 s2, s2, 4
	s_mul_i32 s24, s2, 30
	s_sub_i32 s26, s1, s24
	s_cmpk_gt_u32 s0, 0x1df
	v_readlane_b32 s52, v255, 5
	v_mov_b32_e32 v0, v195
	s_cselect_b32 s0, 0xf00000, 0
	v_readlane_b32 s60, v255, 13
	s_cselect_b32 s1, 0x780000, 0
	v_readlane_b32 s61, v255, 14
	s_add_u32 s24, s60, s0
	v_ashrrev_i32_e32 v20, 8, v0
	v_bfe_u32 v21, v0, 2, 6
	v_lshlrev_b32_e32 v0, 4, v0
	s_addc_u32 s25, s61, 0
	v_and_b32_e32 v22, 48, v0
	v_lshl_or_b32 v0, s2, 6, v21
	s_movk_i32 s27, 0xf00
	s_add_u32 s0, s12, s1
	v_mul_lo_u32 v0, v0, s27
	s_addc_u32 s1, s13, 0
	v_lshl_add_u64 v[2:3], v[0:1], 2, s[24:25]
	s_lshl_b32 s24, s26, 7
	v_lshl_add_u32 v18, v20, 6, s24
	v_ashrrev_i32_e32 v19, 31, v18
	v_lshl_add_u64 v[2:3], v[18:19], 2, v[2:3]
	v_lshlrev_b32_e32 v0, 2, v22
	v_lshl_add_u64 v[14:15], v[2:3], 0, v[0:1]
	s_cmpk_lt_u32 s23, 0x1c0
	s_cbranch_scc1 .Ltp_ld
	s_waitcnt vmcnt(2)
	v_mov_b32_e32 v2, v52
	v_mov_b32_e32 v3, v53
	v_mov_b32_e32 v4, v54
	v_mov_b32_e32 v5, v55
	v_mov_b32_e32 v6, v56
	v_mov_b32_e32 v7, v57
	v_mov_b32_e32 v8, v58
	v_mov_b32_e32 v9, v59
	v_mov_b32_e32 v10, v60
	v_mov_b32_e32 v11, v61
	v_mov_b32_e32 v12, v62
	v_mov_b32_e32 v13, v63
	v_mov_b32_e32 v14, v64
	v_mov_b32_e32 v15, v65
	v_mov_b32_e32 v16, v66
	v_mov_b32_e32 v17, v67
	s_branch .Ltp_pf
.Ltp_ld:
	global_load_dwordx4 v[2:5], v[14:15], off
	global_load_dwordx4 v[6:9], v[14:15], off offset:16
	global_load_dwordx4 v[10:13], v[14:15], off offset:32
	s_nop 0
	global_load_dwordx4 v[14:17], v[14:15], off offset:48
.Ltp_pf:
	s_add_i32 s68, s23, 0x100
	s_cmpk_gt_u32 s68, 0x47f
	s_cselect_b32 s68, s23, s68
	s_add_i32 s69, s68, 0xfffffd60
	s_add_i32 s68, s68, 0xffffff40
	s_cmpk_lt_u32 s68, 0x1e0
	s_cselect_b32 s69, s68, s69
	s_mul_hi_u32 s70, s69, 0x88888889
	s_lshr_b32 s70, s70, 4
	s_mul_i32 s71, s70, 30
	s_sub_i32 s71, s69, s71
	s_cmpk_gt_u32 s68, 0x1df
	s_cselect_b32 s98, 0xf00000, 0
	s_add_u32 s98, s60, s98
	s_addc_u32 s99, s61, 0
	s_movk_i32 s100, 0xf00
	v_lshl_or_b32 v68, s70, 6, v21
	v_mul_lo_u32 v68, v68, s100
	v_mov_b32_e32 v69, 0
	v_lshl_add_u64 v[70:71], v[68:69], 2, s[98:99]
	s_lshl_b32 s101, s71, 7
	v_lshl_add_u32 v72, v20, 6, s101
	v_mov_b32_e32 v73, 0
	v_lshl_add_u64 v[70:71], v[72:73], 2, v[70:71]
	v_lshlrev_b32_e32 v74, 2, v22
	v_mov_b32_e32 v75, 0
	v_lshl_add_u64 v[70:71], v[70:71], 0, v[74:75]
	global_load_dwordx4 v[52:55], v[70:71], off
	global_load_dwordx4 v[56:59], v[70:71], off offset:16
	global_load_dwordx4 v[60:63], v[70:71], off offset:32
	global_load_dwordx4 v[64:67], v[70:71], off offset:48
	s_movk_i32 s24, 0x2400
	v_mul_u32_u24_e32 v19, 0x48, v22
	v_mad_i32_i24 v20, v20, s24, 32
	v_lshlrev_b32_e32 v0, 1, v21
	v_lshlrev_b32_e32 v19, 1, v19
	v_mul_u32_u24_e32 v23, 0x90, v21
	v_add3_u32 v24, v20, v0, v19
	v_add3_u32 v25, v20, v19, v0
	v_lshlrev_b32_e32 v0, 1, v22
	v_or_b32_e32 v18, v18, v21
	v_add3_u32 v20, v20, v23, v0
	v_ashrrev_i32_e32 v19, 31, v18
	v_lshlrev_b64 v[18:19], 11, v[18:19]
	s_lshl_b32 s2, s2, 7
	v_readlane_b32 s53, v255, 6
	v_readlane_b32 s54, v255, 7
	v_readlane_b32 s55, v255, 8
	v_readlane_b32 s56, v255, 9
	v_readlane_b32 s57, v255, 10
	v_readlane_b32 s58, v255, 11
	v_readlane_b32 s59, v255, 12
	v_readlane_b32 s62, v255, 15
	v_readlane_b32 s63, v255, 16
	v_readlane_b32 s64, v255, 17
	v_readlane_b32 s65, v255, 18
	v_readlane_b32 s66, v255, 19
	v_readlane_b32 s67, v255, 20
	s_waitcnt vmcnt(7)
	v_cvt_pk_bf16_f32 v2, v2, v3
	v_cvt_pk_bf16_f32 v3, v4, v5
	s_waitcnt vmcnt(6)
	v_cvt_pk_bf16_f32 v4, v6, v7
	v_cvt_pk_bf16_f32 v5, v8, v9
	s_waitcnt vmcnt(5)
	v_cvt_pk_bf16_f32 v6, v10, v11
	v_cvt_pk_bf16_f32 v7, v12, v13
	s_waitcnt vmcnt(4)
	v_cvt_pk_bf16_f32 v8, v14, v15
	v_cvt_pk_bf16_f32 v9, v16, v17
	ds_write_b16 v24, v2
	ds_write_b16_d16_hi v25, v2 offset:144
	ds_write_b16 v25, v3 offset:288
	ds_write_b16_d16_hi v25, v3 offset:432
	ds_write_b16 v24, v4 offset:576
	ds_write_b16_d16_hi v25, v4 offset:720
	ds_write_b16 v25, v5 offset:864
	ds_write_b16_d16_hi v25, v5 offset:1008
	ds_write_b16 v24, v6 offset:1152
	ds_write_b16_d16_hi v25, v6 offset:1296
	ds_write_b16 v25, v7 offset:1440
	ds_write_b16_d16_hi v25, v7 offset:1584
	ds_write_b16 v24, v8 offset:1728
	ds_write_b16_d16_hi v25, v8 offset:1872
	ds_write_b16 v25, v9 offset:2016
	ds_write_b16_d16_hi v25, v9 offset:2160
	s_waitcnt lgkmcnt(0)
	s_barrier
	ds_read_b128 v[2:5], v20
	ds_read_b128 v[6:9], v20 offset:16
	v_lshl_add_u64 v[10:11], s[0:1], 0, v[18:19]
	v_lshl_add_u64 v[10:11], v[10:11], 0, s[2:3]
	v_lshl_add_u64 v[10:11], v[10:11], 0, v[0:1]
	s_waitcnt lgkmcnt(1)
	global_store_dwordx4 v[10:11], v[2:5], off
	s_waitcnt lgkmcnt(0)
	global_store_dwordx4 v[10:11], v[6:9], off offset:16
	s_barrier
